# P5 A1 Gram stage hand-scheduled (shared Y fragments, reads up front, counted waits) on top of a2+raw+prm+q
# baseline (speedup 1.0000x reference)
; #define LAS __attribute__((address_space(3)))
; __device__ __forceinline__ unsigned pk2(float lo, float hi) { f32x2_k v = {lo, hi}; bf16x2_k b = __builtin_convertvector(v, bf16x2_k); return __builtin_bit_cast(unsigned, b); }
; __device__ __forceinline__ unsigned f2bf(float f) { return pk2(f, 0.f) & 0xffffu; }
; __device__ __forceinline__ void rwkv_chunk_group(Frame& F, int bc, unsigned long long& tsub) {
;     ...
;         float offs = 0.f, tot = 0.f;
; #pragma unroll
;         for (int g = 0; g < 8; ++g) { const float x = *(const LAS float*)(L + L_GT + (g * 64 + ch) * 4); if (g < w) offs += x; tot += x; }
;         const float etot = __expf(tot);
;         if (w == 0) *(LAS float*)(L + L_WC + ch * 4) = etot;
;         unsigned patt[4], pvt[4], pbh[4], pkh[4]; float hAt = 0.f, hBh = 0.f, hKh = 0.f;
;         float e_ex = __expf(offs);
; #pragma unroll
;         for (int tt = 0; tt < 8; ++tt) { const int t = tb + tt; const float cl = offs + ld[tt];
;             const float e_in = __expf(cl), e_inv = __builtin_amdgcn_rcpf(e_in), e_hat = etot * e_inv;
;             const float At = aa[tt] * e_ex, Bt = bb[tt] * e_inv, Kt = kp[tt] * e_inv, Rt = rr[tt] * e_in, Bh = bb[tt] * e_hat, Kh = kp[tt] * e_hat; e_ex = e_in;
;             *(LAS bf16*)(L + L_AT + t * LD + ch * 2) = (bf16)f2bf(At); *(LAS bf16*)(L + L_BT + t * LD + ch * 2) = (bf16)f2bf(Bt);
;             *(LAS bf16*)(L + L_KT + t * LD + ch * 2) = (bf16)f2bf(Kt); *(LAS bf16*)(L + L_RT + t * LD + ch * 2) = (bf16)f2bf(Rt);
;             if (tt & 1) { patt[tt >> 1] = pk2(hAt, At); pvt[tt >> 1] = pk2(vv[tt - 1], vv[tt]); pbh[tt >> 1] = pk2(hBh, Bh); pkh[tt >> 1] = pk2(hKh, Kh); }
;             hAt = At; hBh = Bh; hKh = Kh;
;         }
;         *(LAS v4u*)(L + L_ATT + ch * LD + tb * 2) = (v4u){patt[0], patt[1], patt[2], patt[3]};
;         *(LAS v4u*)(L + L_VT + ch * LD + tb * 2) = (v4u){pvt[0], pvt[1], pvt[2], pvt[3]};
;         *(LAS v4u*)(L + L_BH + ch * LD + tb * 2) = (v4u){pbh[0], pbh[1], pbh[2], pbh[3]};
;         *(LAS v4u*)(L + L_KH + ch * LD + tb * 2) = (v4u){pkh[0], pkh[1], pkh[2], pkh[3]};
.LBB0_1418:
	v_cndmask_b32_e64 v182, v185, 0, s[82:83]
	v_readlane_b32 s66, v254, 40
	v_add_f32_e32 v47, v47, v182
	v_readlane_b32 s67, v254, 41
	s_or_b64 vcc, s[40:41], s[50:51]
	s_mov_b32 s17, s16
	v_cndmask_b32_e64 v47, v182, v47, s[66:67]
	v_readlane_b32 s66, v254, 42
	v_add_f32_e32 v102, v102, v47
	v_readlane_b32 s67, v254, 43
	s_nop 1
	v_cndmask_b32_e64 v47, v47, v102, s[66:67]
	v_readlane_b32 s66, v254, 44
	v_add_f32_e32 v102, v103, v47
	v_readlane_b32 s67, v254, 45
	s_nop 1
	v_cndmask_b32_e64 v47, v47, v102, s[66:67]
	v_readlane_b32 s66, v254, 46
	v_add_f32_e32 v98, v98, v47
	v_readlane_b32 s67, v254, 47
	s_nop 1
	v_cndmask_b32_e64 v47, v47, v98, s[66:67]
	v_readlane_b32 s66, v254, 48
	v_add_f32_e32 v98, v99, v47
	v_readlane_b32 s67, v254, 49
	v_max_f32_e64 v99, s77, s77
	v_max_f32_e32 v99, 0x179abe15, v99
	v_cndmask_b32_e64 v47, v47, v98, s[66:67]
	v_readlane_b32 s66, v254, 50
	v_max_f32_e64 v98, s71, s71
	v_add_f32_e32 v96, v96, v47
	v_readlane_b32 s67, v254, 51
	v_max_f32_e32 v98, 0x179abe15, v98
	v_rsq_f32_e32 v98, v98
	v_cndmask_b32_e64 v47, v47, v96, s[66:67]
	v_rsq_f32_e32 v99, v99
	v_add_f32_e32 v102, v97, v47
	v_max_f32_e64 v97, s14, s14
	v_readlane_b32 s14, v254, 53
	v_readlane_b32 s15, v254, 54
	v_pk_mul_f32 v[88:89], v[88:89], v[98:99]
	v_max_f32_e64 v98, s69, s69
	v_cndmask_b32_e64 v47, v47, v102, s[14:15]
	v_max_f32_e64 v99, s70, s70
	v_add_f32_e32 v102, v177, v47
	v_max_f32_e32 v98, 0x179abe15, v98
	v_max_f32_e32 v99, 0x179abe15, v99
	v_mul_f32_e32 v102, 0x3fb8aa3b, v102
	v_max_f32_e64 v96, s93, s93
	v_rsq_f32_e32 v98, v98
	v_rsq_f32_e32 v99, v99
	v_exp_f32_e32 v103, v102
	v_max_f32_e32 v96, 0x179abe15, v96
	v_max_f32_e32 v97, 0x179abe15, v97
	v_rsq_f32_e32 v96, v96
	v_rsq_f32_e32 v97, v97
	v_pk_mul_f32 v[98:99], v[80:81], v[98:99]
	v_rcp_f32_e32 v80, v103
	v_mul_f32_e32 v81, 0x3fb8aa3b, v47
	v_pk_mul_f32 v[96:97], v[100:101], v[96:97]
	v_exp_f32_e32 v102, v81
	v_pk_mul_f32 v[38:39], v[38:39], v[96:97]
	s_mul_i32 s14, s16, 0x480
	v_mul_f32_e32 v81, v38, v80
	v_pk_mul_f32 v[186:187], v[86:87], v[98:99]
	v_mul_f32_e32 v86, v40, v80
	v_mul_f32_e32 v87, v173, v103
	v_cvt_pk_bf16_f32 v81, v81, s0
	v_add_u32_e32 v173, s14, v58
	ds_write_b16 v173, v81 offset:9216
	v_cvt_pk_bf16_f32 v81, v86, s0
	v_add_f32_e32 v86, v176, v47
	v_mul_f32_e32 v86, 0x3fb8aa3b, v86
	v_max_f32_e64 v100, s64, s64
	v_max_f32_e64 v101, s65, s65
	v_exp_f32_e32 v176, v86
	v_max_f32_e32 v100, 0x179abe15, v100
	v_max_f32_e32 v101, 0x179abe15, v101
	v_rsq_f32_e32 v100, v100
	v_rsq_f32_e32 v101, v101
	ds_write_b16 v173, v81 offset:18432
	v_cvt_pk_bf16_f32 v81, v87, s0
	ds_write_b16 v173, v81 offset:27648
	v_rcp_f32_e32 v81, v176
	v_pk_mul_f32 v[44:45], v[44:45], v[100:101]
	v_pk_mul_f32 v[86:87], v[102:103], v[96:97] neg_lo:[0,1] neg_hi:[0,1]
	v_pk_mul_f32 v[100:101], v[94:95], v[44:45]
	v_cvt_pk_bf16_f32 v94, v86, s0
	ds_write_b16 v173, v94
	v_mul_f32_e32 v94, v39, v81
	v_mul_f32_e32 v95, v41, v81
	v_cvt_pk_bf16_f32 v94, v94, s0
	v_mul_f32_e32 v96, v174, v176
	ds_write_b16 v173, v94 offset:9360
	v_cvt_pk_bf16_f32 v94, v95, s0
	ds_write_b16 v173, v94 offset:18576
	v_cvt_pk_bf16_f32 v94, v96, s0
	ds_write_b16 v173, v94 offset:27792
	v_add_f32_e32 v94, v179, v47
	v_mul_f32_e32 v94, 0x3fb8aa3b, v94
	v_exp_f32_e32 v177, v94
	v_pk_mul_f32 v[82:83], v[82:83], v[88:89]
	v_pk_mul_f32 v[80:81], v[46:47], v[80:81] op_sel_hi:[0,1]
	v_pk_mul_f32 v[40:41], v[40:41], v[80:81]
	v_rcp_f32_e32 v96, v177
	v_pk_mul_f32 v[94:95], v[38:39], v[80:81]
	v_cvt_pk_bf16_f32 v80, v36, v37
	v_cvt_pk_bf16_f32 v97, v87, s0
	v_mul_f32_e32 v36, v82, v96
	v_cvt_pk_bf16_f32 v36, v36, s0
	ds_write_b16 v173, v36 offset:9504
	v_add_f32_e32 v36, v181, v47
	v_mul_f32_e32 v36, 0x3fb8aa3b, v36
	v_exp_f32_e32 v36, v36
	ds_write_b16 v173, v97 offset:144
	v_mul_f32_e32 v37, v78, v96
	v_mul_f32_e32 v39, v175, v177
	v_rcp_f32_e32 v97, v36
	v_cvt_pk_bf16_f32 v37, v37, s0
	v_cvt_pk_bf16_f32 v38, v86, v87
	v_cvt_pk_bf16_f32 v86, v94, v95
	v_cvt_pk_bf16_f32 v94, v40, v41
	ds_write_b16 v173, v37 offset:18720
	v_cvt_pk_bf16_f32 v37, v39, s0
	v_pk_mul_f32 v[40:41], v[176:177], v[88:89] neg_lo:[0,1] neg_hi:[0,1]
	ds_write_b16 v173, v37 offset:27936
	v_cvt_pk_bf16_f32 v37, v40, s0
	ds_write_b16 v173, v37 offset:288
	v_mul_f32_e32 v37, v83, v97
	v_mul_f32_e32 v39, v79, v97
	v_cvt_pk_bf16_f32 v37, v37, s0
	v_mul_f32_e32 v81, v178, v36
	ds_write_b16 v173, v37 offset:9648
	v_cvt_pk_bf16_f32 v37, v39, s0
	ds_write_b16 v173, v37 offset:18864
	v_cvt_pk_bf16_f32 v37, v81, s0
	ds_write_b16 v173, v37 offset:28080
	v_add_f32_e32 v37, v184, v47
	v_mul_f32_e32 v37, 0x3fb8aa3b, v37
	v_exp_f32_e32 v37, v37
	v_cvt_pk_bf16_f32 v39, v40, v41
	v_cvt_pk_bf16_f32 v87, v41, s0
	v_cvt_pk_bf16_f32 v81, v76, v77
	v_rcp_f32_e32 v40, v37
	v_mul_f32_e32 v77, v180, v37
	v_pk_mul_f32 v[36:37], v[36:37], v[98:99] neg_lo:[0,1] neg_hi:[0,1]
	v_pk_mul_f32 v[88:89], v[46:47], v[96:97] op_sel_hi:[0,1]
	v_mul_f32_e32 v41, v186, v40
	v_mul_f32_e32 v76, v90, v40
	v_cvt_pk_bf16_f32 v41, v41, s0
	ds_write_b16 v173, v41 offset:9792
	v_cvt_pk_bf16_f32 v41, v76, s0
	v_add_f32_e32 v76, v190, v47
	v_mul_f32_e32 v76, 0x3fb8aa3b, v76
	v_exp_f32_e32 v76, v76
	ds_write_b16 v173, v41 offset:19008
	v_cvt_pk_bf16_f32 v41, v77, s0
	ds_write_b16 v173, v41 offset:28224
	v_rcp_f32_e32 v41, v76
	v_cvt_pk_bf16_f32 v77, v36, s0
	v_pk_mul_f32 v[78:79], v[78:79], v[88:89]
	ds_write_b16 v173, v77 offset:576
	v_mul_f32_e32 v77, v187, v41
	v_cvt_pk_bf16_f32 v95, v78, v79
	v_mul_f32_e32 v78, v91, v41
	v_cvt_pk_bf16_f32 v77, v77, s0
	v_mul_f32_e32 v79, v183, v76
	ds_write_b16 v173, v77 offset:9936
	v_cvt_pk_bf16_f32 v77, v78, s0
	ds_write_b16 v173, v77 offset:19152
; __device__ __forceinline__ void st4_lds(LAS unsigned char* p, f32x4 v) { v2u w; w.x = pk2(v[0], v[1]); w.y = pk2(v[2], v[3]); *(LAS v2u*)p = w; }
; #define LBAR() asm volatile("s_waitcnt lgkmcnt(0)\n\ts_barrier" ::: "memory")
; __device__ __forceinline__ void rwkv_chunk_group(Frame& F, int bc, unsigned long long& tsub) {
;     ...
; #pragma unroll
;     for (int q = 0; q < 2; ++q) { const int tw = 2 * w + q, p0 = 16 * (tw >> 2), q0 = 16 * (tw & 3);
;         f32x4 m = mm_tile(L + L_AT, LD, q0, L + L_BT, LD, p0, 2, Z4, fr, fq);
;         f32x4 nak = mm_tile(L + L_KT, LD, q0, L + L_AT, LD, p0, 2, Z4, fr, fq);
;         f32x4 nrk = mm_tile(L + L_KT, LD, q0, L + L_RT, LD, p0, 2, Z4, fr, fq);
;         f32x4 nrb = mm_tile(L + L_BT, LD, q0, L + L_RT, LD, p0, 2, Z4, fr, fq);
;         f32x4 tt;
;         const int p = p0 + fr;
; #pragma unroll
;         for (int v = 0; v < 4; ++v) { const int qq = q0 + 4 * fq + v;
;             if (!(p < qq)) m[v] = 0.f;
;             if (!(qq < p)) nak[v] = 0.f;
;             if (!(qq <= p)) { nrk[v] = 0.f; nrb[v] = 0.f; }
;             tt[v] = (p == qq) ? 1.f : 0.f; }
;         const int o = p * LD + (q0 + 4 * fq) * 2;
;         st4_lds(L + L_M + o, m); st4t_lds(L + L_MT, p, q0 + 4 * fq, m); st4_lds(L + L_NAK + o, nak); st4_lds(L + L_NRK + o, nrk); st4_lds(L + L_NRB + o, nrb); st4_lds(L + L_TT + o, tt);
;     }
;     LBAR();
	v_cvt_pk_bf16_f32 v77, v79, s0
	ds_write_b16 v173, v77 offset:28368
	v_add_f32_e32 v77, v192, v47
	v_mul_f32_e32 v77, 0x3fb8aa3b, v77
	v_exp_f32_e32 v77, v77
	v_pk_mul_f32 v[40:41], v[46:47], v[40:41] op_sel_hi:[0,1]
	v_pk_mul_f32 v[82:83], v[82:83], v[88:89]
	v_pk_mul_f32 v[78:79], v[90:91], v[40:41]
	v_pk_mul_f32 v[88:89], v[186:187], v[40:41]
	v_cvt_pk_bf16_f32 v40, v36, v37
	v_rcp_f32_e32 v36, v77
	ds_write_b16 v173, v87 offset:432
	v_cvt_pk_bf16_f32 v87, v82, v83
	v_cvt_pk_bf16_f32 v82, v37, s0
	v_mul_f32_e32 v37, v100, v36
	v_mul_f32_e32 v41, v42, v36
	v_cvt_pk_bf16_f32 v37, v37, s0
	ds_write_b16 v173, v37 offset:10080
	v_cvt_pk_bf16_f32 v37, v41, s0
	v_add_f32_e32 v41, v52, v47
	v_mul_f32_e32 v41, 0x3fb8aa3b, v41
	v_exp_f32_e32 v41, v41
	v_cvt_pk_bf16_f32 v96, v78, v79
	v_mul_f32_e32 v78, v188, v77
	ds_write_b16 v173, v37 offset:19296
	v_cvt_pk_bf16_f32 v37, v78, s0
	ds_write_b16 v173, v37 offset:28512
	v_rcp_f32_e32 v37, v41
	v_pk_mul_f32 v[44:45], v[76:77], v[44:45] neg_lo:[0,1] neg_hi:[0,1]
	v_mul_f32_e32 v41, v191, v41
	v_cvt_pk_bf16_f32 v47, v44, s0
	ds_write_b16 v173, v47 offset:864
	v_mul_f32_e32 v47, v101, v37
	v_mul_f32_e32 v52, v43, v37
	v_cvt_pk_bf16_f32 v47, v47, s0
	ds_write_b16 v173, v47 offset:10224
	v_cvt_pk_bf16_f32 v47, v52, s0
	v_cvt_pk_bf16_f32 v41, v41, s0
	v_pk_mul_f32 v[36:37], v[46:47], v[36:37] op_sel_hi:[0,1]
	v_cvt_pk_bf16_f32 v76, v45, s0
	ds_write_b16 v173, v41 offset:28656
	v_pk_mul_f32 v[42:43], v[42:43], v[36:37]
	v_pk_mul_f32 v[36:37], v[100:101], v[36:37]
	v_cvt_pk_bf16_f32 v41, v44, v45
	ds_write_b16 v173, v82 offset:720
	v_cvt_pk_bf16_f32 v82, v84, v85
	v_cvt_pk_bf16_f32 v88, v88, v89
	ds_write_b16 v173, v76 offset:1008
	ds_write_b16 v173, v47 offset:19440
	v_cvt_pk_bf16_f32 v97, v42, v43
	v_cvt_pk_bf16_f32 v89, v36, v37
	v_cvt_pk_bf16_f32 v83, v92, v93
	ds_write_b128 v141, v[38:41] offset:36864
	ds_write_b128 v141, v[80:83] offset:46080
	ds_write_b128 v141, v[86:89] offset:55296
	ds_write_b128 v141, v[94:97] offset:64512
	s_waitcnt lgkmcnt(0)
	s_barrier
	v_add_u32_e32 v76, v106, v110
	v_add_u32_e32 v77, v106, v128
	v_add_u32_e32 v97, 0x12000, v127
	v_add_u32_e32 v98, 0x12000, v129
	ds_read_b128 v[176:179], v76 offset:0
	ds_read_b128 v[224:227], v107 offset:9216
	ds_read_b128 v[184:187], v76 offset:18432
	ds_read_b128 v[232:235], v107 offset:0
	ds_read_b128 v[240:243], v107 offset:27648
	ds_read_b128 v[192:195], v76 offset:9216
	ds_read_b128 v[180:183], v76 offset:64
	ds_read_b128 v[228:231], v107 offset:9280
	ds_read_b128 v[188:191], v76 offset:18496
	ds_read_b128 v[236:239], v107 offset:64
	ds_read_b128 v[244:247], v107 offset:27712
	ds_read_b128 v[196:199], v76 offset:9280
	s_waitcnt lgkmcnt(10)
	v_mfma_f32_16x16x32_bf16 v[78:81], v[176:179], v[224:227], 0
	s_waitcnt lgkmcnt(8)
	v_mfma_f32_16x16x32_bf16 v[82:85], v[184:187], v[232:235], 0
	s_waitcnt lgkmcnt(7)
	v_mfma_f32_16x16x32_bf16 v[86:89], v[184:187], v[240:243], 0
	s_waitcnt lgkmcnt(6)
	v_mfma_f32_16x16x32_bf16 v[90:93], v[192:195], v[240:243], 0
	s_waitcnt lgkmcnt(4)
	v_mfma_f32_16x16x32_bf16 v[78:81], v[180:183], v[228:231], v[78:81]
	s_waitcnt lgkmcnt(2)
	v_mfma_f32_16x16x32_bf16 v[82:85], v[188:191], v[236:239], v[82:85]
	s_waitcnt lgkmcnt(1)
	v_mfma_f32_16x16x32_bf16 v[86:89], v[188:191], v[244:247], v[86:89]
	s_waitcnt lgkmcnt(0)
	v_mfma_f32_16x16x32_bf16 v[90:93], v[196:199], v[244:247], v[90:93]
	ds_read_b128 v[176:179], v77 offset:0
	ds_read_b128 v[184:187], v77 offset:18432
	ds_read_b128 v[192:195], v77 offset:9216
	ds_read_b128 v[180:183], v77 offset:64
	ds_read_b128 v[188:191], v77 offset:18496
	ds_read_b128 v[196:199], v77 offset:9280
	s_nop 1
	v_cndmask_b32_e64 v78, 0, v78, s[48:49]
	v_cndmask_b32_e64 v79, v79, 0, s[50:51]
	v_cndmask_b32_e64 v80, 0, v80, s[52:53]
	v_cndmask_b32_e64 v81, 0, v81, s[54:55]
	v_cndmask_b32_e64 v82, 0, v82, s[50:51]
	v_cndmask_b32_e64 v83, 0, v83, s[40:41]
	v_cndmask_b32_e64 v84, 0, v84, s[38:39]
	v_cndmask_b32_e64 v85, 0, v85, s[36:37]
	v_cndmask_b32_e64 v86, v86, 0, s[48:49]
	v_cndmask_b32_e64 v87, 0, v87, s[50:51]
	v_cndmask_b32_e64 v88, v88, 0, s[52:53]
	v_cndmask_b32_e64 v89, v89, 0, s[54:55]
	v_cndmask_b32_e64 v90, v90, 0, s[48:49]
	v_cndmask_b32_e64 v91, 0, v91, s[50:51]
	v_cndmask_b32_e64 v92, v92, 0, s[52:53]
	v_cndmask_b32_e64 v93, v93, 0, s[54:55]
	v_cvt_pk_bf16_f32 v78, v78, v79
	v_cvt_pk_bf16_f32 v79, v80, v81
	v_cvt_pk_bf16_f32 v82, v82, v83
	v_cvt_pk_bf16_f32 v83, v84, v85
	v_cvt_pk_bf16_f32 v86, v86, v87
	v_cvt_pk_bf16_f32 v87, v88, v89
	v_cvt_pk_bf16_f32 v90, v90, v91
	v_cvt_pk_bf16_f32 v91, v92, v93
	ds_write_b64 v97, v[78:79]
	ds_write_b16 v148, v78
	ds_write_b16_d16_hi v148, v78 offset:144
	ds_write_b16 v148, v79 offset:288
	ds_write_b16_d16_hi v148, v79 offset:432
	ds_write_b64 v97, v[82:83] offset:27648
	ds_write_b64 v97, v[86:87] offset:36864
	ds_write_b64 v97, v[90:91] offset:46080
	ds_write_b64 v97, v[60:61] offset:18432
	s_waitcnt lgkmcnt(14)
	v_mfma_f32_16x16x32_bf16 v[36:39], v[176:179], v[224:227], 0
	s_waitcnt lgkmcnt(13)
	v_mfma_f32_16x16x32_bf16 v[40:43], v[184:187], v[232:235], 0
	s_waitcnt lgkmcnt(13)
	v_mfma_f32_16x16x32_bf16 v[44:47], v[184:187], v[240:243], 0
	s_waitcnt lgkmcnt(12)
	v_mfma_f32_16x16x32_bf16 v[100:103], v[192:195], v[240:243], 0
	s_waitcnt lgkmcnt(11)
	v_mfma_f32_16x16x32_bf16 v[36:39], v[180:183], v[228:231], v[36:39]
	s_waitcnt lgkmcnt(10)
	v_mfma_f32_16x16x32_bf16 v[40:43], v[188:191], v[236:239], v[40:43]
	s_waitcnt lgkmcnt(10)
	v_mfma_f32_16x16x32_bf16 v[44:47], v[188:191], v[244:247], v[44:47]
	s_waitcnt lgkmcnt(9)
	v_mfma_f32_16x16x32_bf16 v[100:103], v[196:199], v[244:247], v[100:103]
	s_nop 7
	v_cndmask_b32_e64 v36, 0, v36, s[56:57]
	v_cndmask_b32_e64 v37, v37, 0, s[58:59]
	v_cndmask_b32_e64 v38, 0, v38, s[60:61]
	v_cndmask_b32_e64 v39, 0, v39, s[62:63]
	v_cndmask_b32_e64 v40, 0, v40, s[58:59]
	v_cndmask_b32_e64 v41, 0, v41, s[46:47]
	v_cndmask_b32_e64 v42, 0, v42, s[44:45]
	v_cndmask_b32_e64 v43, 0, v43, s[42:43]
	v_cndmask_b32_e64 v44, v44, 0, s[56:57]
	v_cndmask_b32_e64 v45, 0, v45, s[58:59]
	v_cndmask_b32_e64 v46, v46, 0, s[60:61]
	v_cndmask_b32_e64 v47, v47, 0, s[62:63]
	v_cndmask_b32_e64 v100, v100, 0, s[56:57]
	v_cndmask_b32_e64 v101, 0, v101, s[58:59]
	v_cndmask_b32_e64 v102, v102, 0, s[60:61]
	v_cndmask_b32_e64 v103, v103, 0, s[62:63]
	v_cvt_pk_bf16_f32 v36, v36, v37
	v_cvt_pk_bf16_f32 v37, v38, v39
	v_cvt_pk_bf16_f32 v40, v40, v41
	v_cvt_pk_bf16_f32 v41, v42, v43
	v_cvt_pk_bf16_f32 v44, v44, v45
	v_cvt_pk_bf16_f32 v45, v46, v47
	v_cvt_pk_bf16_f32 v100, v100, v101
	v_cvt_pk_bf16_f32 v101, v102, v103
	ds_write_b64 v98, v[36:37]
	ds_write_b16 v149, v36
	ds_write_b16_d16_hi v149, v36 offset:144
	ds_write_b16 v149, v37 offset:288
	ds_write_b16_d16_hi v149, v37 offset:432
	ds_write_b64 v98, v[40:41] offset:27648
	ds_write_b64 v98, v[44:45] offset:36864
	ds_write_b64 v98, v[100:101] offset:46080
	ds_write_b64 v98, v[72:73] offset:18432
	s_andn2_b64 vcc, exec, s[78:79]
	s_waitcnt lgkmcnt(0)
	s_barrier
; __device__ __forceinline__ void st4_lds(LAS unsigned char* p, f32x4 v) { v2u w; w.x = pk2(v[0], v[1]); w.y = pk2(v[2], v[3]); *(LAS v2u*)p = w; }
; __device__ __forceinline__ f32x4 ld4_lds(const LAS unsigned char* p) { const v2u w = *(const LAS v2u*)p; return (f32x4){bflo(w.x), bfhi(w.x), bflo(w.y), bfhi(w.y)}; }
; #define LBAR() asm volatile("s_waitcnt lgkmcnt(0)\n\ts_barrier" ::: "memory")
; __device__ __forceinline__ void rwkv_chunk_group(Frame& F, int bc, unsigned long long& tsub) {
;     ...
;     for (int it = 0; it < 6; ++it) {
;         const int rM = (it & 1) ? L_AT : L_M, rMT = (it & 1) ? L_BT : L_MT, rTT = (it & 1) ? L_KT : L_TT;
;         const int wM = (it & 1) ? L_M : L_AT, wMT = (it & 1) ? L_MT : L_BT, wTT = (it & 1) ? L_TT : L_KT;
; #pragma unroll
;         for (int q = 0; q < 2; ++q) { const int tw = 2 * w + q, p0 = 16 * (tw >> 2), q0 = 16 * (tw & 3); const int o = (p0 + fr) * LD + (q0 + 4 * fq) * 2;
;             f32x4 tn = Z4, mn = Z4;
;             if (q0 <= p0) { tn = mm_tile(L + rM, LD, q0, L + rTT, LD, p0, 2, ld4_lds(L + rTT + o), fr, fq);
;                           }
;             if (q0 >= p0 && it < 5) mn = mm_tile(L + rMT, LD, q0, L + rM, LD, p0, 2, Z4, fr, fq);
;             st4_lds(L + wTT + o, tn); if (it < 5) { st4_lds(L + wM + o, mn); st4t_lds(L + wMT, p0 + fr, q0 + 4 * fq, mn); } }
;         LBAR();
;     }
	v_mov_b32_e32 v78, v127
	v_mov_b32_e32 v79, v129
	v_add_u32_e32 v173, v106, v110
	v_add_u32_e32 v174, v106, v128
	v_add_u32_e32 v97, 0x12000, v127
	v_add_u32_e32 v98, 0x12000, v129
	v_mov_b32_e32 v102, 0
	v_mov_b32_e32 v103, 0
	v_add_u32_e32 v175, 0x12000, v173
	v_add_u32_e32 v96, 0x12000, v174
	s_and_b64 vcc, exec, s[78:79]
	s_cbranch_vccz .La2_FTFT
	s_and_b64 vcc, exec, s[84:85]
	s_cbranch_vccz .La2_TFTx
	ds_read_b64 v[242:243], v97 offset:18432
	ds_read_b128 v[176:179], v175 offset:0
	ds_read_b128 v[224:227], v132 offset:18432
	ds_read_b128 v[184:187], v175 offset:9216
	ds_read_b128 v[232:235], v132 offset:0
	ds_read_b128 v[192:195], v96 offset:9216
	ds_read_b128 v[180:183], v175 offset:64
	ds_read_b128 v[228:231], v132 offset:18496
	ds_read_b128 v[188:191], v175 offset:9280
	ds_read_b128 v[236:239], v132 offset:64
	ds_read_b128 v[196:199], v96 offset:9280
	s_waitcnt lgkmcnt(10)
	v_lshlrev_b32_e32 v240, 16, v242
	v_and_b32_e32 v241, 0xffff0000, v242
	v_lshlrev_b32_e32 v242, 16, v243
	v_and_b32_e32 v243, 0xffff0000, v243
	s_nop 1
	s_waitcnt lgkmcnt(8)
	v_mfma_f32_16x16x32_bf16 v[240:243], v[176:179], v[224:227], v[240:243]
	s_waitcnt lgkmcnt(6)
	v_mfma_f32_16x16x32_bf16 v[244:247], v[184:187], v[232:235], 0
	s_waitcnt lgkmcnt(5)
	v_mfma_f32_16x16x32_bf16 v[248:251], v[192:195], v[232:235], 0
	s_waitcnt lgkmcnt(3)
	v_mfma_f32_16x16x32_bf16 v[240:243], v[180:183], v[228:231], v[240:243]
	s_waitcnt lgkmcnt(1)
	v_mfma_f32_16x16x32_bf16 v[244:247], v[188:191], v[236:239], v[244:247]
	s_waitcnt lgkmcnt(0)
	v_mfma_f32_16x16x32_bf16 v[248:251], v[196:199], v[236:239], v[248:251]
	s_nop 7
	v_cvt_pk_bf16_f32 v176, v240, v241
	v_cvt_pk_bf16_f32 v177, v242, v243
	v_cvt_pk_bf16_f32 v184, v244, v245
	v_cvt_pk_bf16_f32 v185, v246, v247
	v_cvt_pk_bf16_f32 v192, v248, v249
	v_cvt_pk_bf16_f32 v193, v250, v251
	ds_write_b64 v127, v[176:177] offset:18432
	ds_write_b64 v127, v[184:185] offset:0
	ds_write_b16 v151, v184 offset:9216
	ds_write_b16_d16_hi v151, v184 offset:9360
	ds_write_b16 v151, v185 offset:9504
	ds_write_b16_d16_hi v151, v185 offset:9648
	ds_write_b64 v129, v[102:103] offset:18432
	ds_write_b64 v129, v[192:193] offset:0
	ds_write_b16 v152, v192 offset:9216
	ds_write_b16_d16_hi v152, v192 offset:9360
	ds_write_b16 v152, v193 offset:9504
	ds_write_b16_d16_hi v152, v193 offset:9648
	s_waitcnt lgkmcnt(0)
	s_barrier
	ds_read_b64 v[242:243], v127 offset:18432
	ds_read_b128 v[176:179], v173 offset:0
	ds_read_b128 v[224:227], v107 offset:18432
	ds_read_b128 v[184:187], v173 offset:9216
	ds_read_b128 v[232:235], v107 offset:0
	ds_read_b128 v[192:195], v174 offset:9216
	ds_read_b128 v[180:183], v173 offset:64
	ds_read_b128 v[228:231], v107 offset:18496
	ds_read_b128 v[188:191], v173 offset:9280
	ds_read_b128 v[236:239], v107 offset:64
	ds_read_b128 v[196:199], v174 offset:9280
	s_waitcnt lgkmcnt(10)
	v_lshlrev_b32_e32 v240, 16, v242
	v_and_b32_e32 v241, 0xffff0000, v242
	v_lshlrev_b32_e32 v242, 16, v243
	v_and_b32_e32 v243, 0xffff0000, v243
	s_nop 1
	s_waitcnt lgkmcnt(8)
	v_mfma_f32_16x16x32_bf16 v[240:243], v[176:179], v[224:227], v[240:243]
	s_waitcnt lgkmcnt(6)
	v_mfma_f32_16x16x32_bf16 v[244:247], v[184:187], v[232:235], 0
	s_waitcnt lgkmcnt(5)
	v_mfma_f32_16x16x32_bf16 v[248:251], v[192:195], v[232:235], 0
	s_waitcnt lgkmcnt(3)
	v_mfma_f32_16x16x32_bf16 v[240:243], v[180:183], v[228:231], v[240:243]
	s_waitcnt lgkmcnt(1)
	v_mfma_f32_16x16x32_bf16 v[244:247], v[188:191], v[236:239], v[244:247]
	s_waitcnt lgkmcnt(0)
	v_mfma_f32_16x16x32_bf16 v[248:251], v[196:199], v[236:239], v[248:251]
	s_nop 7
	v_cvt_pk_bf16_f32 v176, v240, v241
	v_cvt_pk_bf16_f32 v177, v242, v243
	v_cvt_pk_bf16_f32 v184, v244, v245
	v_cvt_pk_bf16_f32 v185, v246, v247
	v_cvt_pk_bf16_f32 v192, v248, v249
	v_cvt_pk_bf16_f32 v193, v250, v251
	ds_write_b64 v97, v[176:177] offset:18432
	ds_write_b64 v97, v[184:185] offset:0
	ds_write_b16 v148, v184 offset:0
	ds_write_b16_d16_hi v148, v184 offset:144
	ds_write_b16 v148, v185 offset:288
	ds_write_b16_d16_hi v148, v185 offset:432
	ds_write_b64 v98, v[102:103] offset:18432
	ds_write_b64 v98, v[192:193] offset:0
	ds_write_b16 v149, v192 offset:0
	ds_write_b16_d16_hi v149, v192 offset:144
	ds_write_b16 v149, v193 offset:288
	ds_write_b16_d16_hi v149, v193 offset:432
	s_waitcnt lgkmcnt(0)
	s_barrier
	ds_read_b64 v[242:243], v97 offset:18432
	ds_read_b128 v[176:179], v175 offset:0
	ds_read_b128 v[224:227], v132 offset:18432
	ds_read_b128 v[184:187], v175 offset:9216
	ds_read_b128 v[232:235], v132 offset:0
	ds_read_b128 v[192:195], v96 offset:9216
	ds_read_b128 v[180:183], v175 offset:64
	ds_read_b128 v[228:231], v132 offset:18496
	ds_read_b128 v[188:191], v175 offset:9280
	ds_read_b128 v[236:239], v132 offset:64
	ds_read_b128 v[196:199], v96 offset:9280
	s_waitcnt lgkmcnt(10)
	v_lshlrev_b32_e32 v240, 16, v242
	v_and_b32_e32 v241, 0xffff0000, v242
	v_lshlrev_b32_e32 v242, 16, v243
	v_and_b32_e32 v243, 0xffff0000, v243
	s_nop 1
	s_waitcnt lgkmcnt(8)
	v_mfma_f32_16x16x32_bf16 v[240:243], v[176:179], v[224:227], v[240:243]
	s_waitcnt lgkmcnt(6)
	v_mfma_f32_16x16x32_bf16 v[244:247], v[184:187], v[232:235], 0
	s_waitcnt lgkmcnt(5)
	v_mfma_f32_16x16x32_bf16 v[248:251], v[192:195], v[232:235], 0
	s_waitcnt lgkmcnt(3)
	v_mfma_f32_16x16x32_bf16 v[240:243], v[180:183], v[228:231], v[240:243]
	s_waitcnt lgkmcnt(1)
	v_mfma_f32_16x16x32_bf16 v[244:247], v[188:191], v[236:239], v[244:247]
	s_waitcnt lgkmcnt(0)
	v_mfma_f32_16x16x32_bf16 v[248:251], v[196:199], v[236:239], v[248:251]
	s_nop 7
	v_cvt_pk_bf16_f32 v176, v240, v241
	v_cvt_pk_bf16_f32 v177, v242, v243
	v_cvt_pk_bf16_f32 v184, v244, v245
	v_cvt_pk_bf16_f32 v185, v246, v247
	v_cvt_pk_bf16_f32 v192, v248, v249
	v_cvt_pk_bf16_f32 v193, v250, v251
	ds_write_b64 v127, v[176:177] offset:18432
	ds_write_b64 v127, v[184:185] offset:0
	ds_write_b16 v151, v184 offset:9216
	ds_write_b16_d16_hi v151, v184 offset:9360
	ds_write_b16 v151, v185 offset:9504
	ds_write_b16_d16_hi v151, v185 offset:9648
	ds_write_b64 v129, v[102:103] offset:18432
	ds_write_b64 v129, v[192:193] offset:0
	ds_write_b16 v152, v192 offset:9216
	ds_write_b16_d16_hi v152, v192 offset:9360
	ds_write_b16 v152, v193 offset:9504
	ds_write_b16_d16_hi v152, v193 offset:9648
	s_waitcnt lgkmcnt(0)
	s_barrier
; __device__ __forceinline__ void st4_lds(LAS unsigned char* p, f32x4 v) { v2u w; w.x = pk2(v[0], v[1]); w.y = pk2(v[2], v[3]); *(LAS v2u*)p = w; }
; __device__ __forceinline__ f32x4 ld4_lds(const LAS unsigned char* p) { const v2u w = *(const LAS v2u*)p; return (f32x4){bflo(w.x), bfhi(w.x), bflo(w.y), bfhi(w.y)}; }
; #define LBAR() asm volatile("s_waitcnt lgkmcnt(0)\n\ts_barrier" ::: "memory")
; __device__ __forceinline__ void rwkv_chunk_group(Frame& F, int bc, unsigned long long& tsub) {
;     ...
;     for (int it = 0; it < 6; ++it) {
;         const int rM = (it & 1) ? L_AT : L_M, rMT = (it & 1) ? L_BT : L_MT, rTT = (it & 1) ? L_KT : L_TT;
;         const int wM = (it & 1) ? L_M : L_AT, wMT = (it & 1) ? L_MT : L_BT, wTT = (it & 1) ? L_TT : L_KT;
; #pragma unroll
;         for (int q = 0; q < 2; ++q) { const int tw = 2 * w + q, p0 = 16 * (tw >> 2), q0 = 16 * (tw & 3); const int o = (p0 + fr) * LD + (q0 + 4 * fq) * 2;
;             f32x4 tn = Z4, mn = Z4;
;             if (q0 <= p0) { tn = mm_tile(L + rM, LD, q0, L + rTT, LD, p0, 2, ld4_lds(L + rTT + o), fr, fq);
;                           }
;             if (q0 >= p0 && it < 5) mn = mm_tile(L + rMT, LD, q0, L + rM, LD, p0, 2, Z4, fr, fq);
;             st4_lds(L + wTT + o, tn); if (it < 5) { st4_lds(L + wM + o, mn); st4t_lds(L + wMT, p0 + fr, q0 + 4 * fq, mn); } }
;         LBAR();
;     }
	ds_read_b64 v[242:243], v127 offset:18432
	ds_read_b128 v[176:179], v173 offset:0
	ds_read_b128 v[224:227], v107 offset:18432
	ds_read_b128 v[184:187], v173 offset:9216
	ds_read_b128 v[232:235], v107 offset:0
	ds_read_b128 v[192:195], v174 offset:9216
	ds_read_b128 v[180:183], v173 offset:64
	ds_read_b128 v[228:231], v107 offset:18496
	ds_read_b128 v[188:191], v173 offset:9280
	ds_read_b128 v[236:239], v107 offset:64
	ds_read_b128 v[196:199], v174 offset:9280
	s_waitcnt lgkmcnt(10)
	v_lshlrev_b32_e32 v240, 16, v242
	v_and_b32_e32 v241, 0xffff0000, v242
	v_lshlrev_b32_e32 v242, 16, v243
	v_and_b32_e32 v243, 0xffff0000, v243
	s_nop 1
	s_waitcnt lgkmcnt(8)
	v_mfma_f32_16x16x32_bf16 v[240:243], v[176:179], v[224:227], v[240:243]
	s_waitcnt lgkmcnt(6)
	v_mfma_f32_16x16x32_bf16 v[244:247], v[184:187], v[232:235], 0
	s_waitcnt lgkmcnt(5)
	v_mfma_f32_16x16x32_bf16 v[248:251], v[192:195], v[232:235], 0
	s_waitcnt lgkmcnt(3)
	v_mfma_f32_16x16x32_bf16 v[240:243], v[180:183], v[228:231], v[240:243]
	s_waitcnt lgkmcnt(1)
	v_mfma_f32_16x16x32_bf16 v[244:247], v[188:191], v[236:239], v[244:247]
	s_waitcnt lgkmcnt(0)
	v_mfma_f32_16x16x32_bf16 v[248:251], v[196:199], v[236:239], v[248:251]
	s_nop 7
	v_cvt_pk_bf16_f32 v176, v240, v241
	v_cvt_pk_bf16_f32 v177, v242, v243
	v_cvt_pk_bf16_f32 v184, v244, v245
	v_cvt_pk_bf16_f32 v185, v246, v247
	v_cvt_pk_bf16_f32 v192, v248, v249
	v_cvt_pk_bf16_f32 v193, v250, v251
	ds_write_b64 v97, v[176:177] offset:18432
	ds_write_b64 v97, v[184:185] offset:0
	ds_write_b16 v148, v184 offset:0
	ds_write_b16_d16_hi v148, v184 offset:144
	ds_write_b16 v148, v185 offset:288
	ds_write_b16_d16_hi v148, v185 offset:432
	ds_write_b64 v98, v[102:103] offset:18432
	ds_write_b64 v98, v[192:193] offset:0
	ds_write_b16 v149, v192 offset:0
	ds_write_b16_d16_hi v149, v192 offset:144
	ds_write_b16 v149, v193 offset:288
	ds_write_b16_d16_hi v149, v193 offset:432
	s_waitcnt lgkmcnt(0)
	s_barrier
	ds_read_b64 v[242:243], v97 offset:18432
	ds_read_b128 v[176:179], v175 offset:0
	ds_read_b128 v[224:227], v132 offset:18432
	ds_read_b128 v[184:187], v175 offset:9216
	ds_read_b128 v[232:235], v132 offset:0
	ds_read_b128 v[192:195], v96 offset:9216
	ds_read_b128 v[180:183], v175 offset:64
	ds_read_b128 v[228:231], v132 offset:18496
	ds_read_b128 v[188:191], v175 offset:9280
	ds_read_b128 v[236:239], v132 offset:64
	ds_read_b128 v[196:199], v96 offset:9280
	s_waitcnt lgkmcnt(10)
	v_lshlrev_b32_e32 v240, 16, v242
	v_and_b32_e32 v241, 0xffff0000, v242
	v_lshlrev_b32_e32 v242, 16, v243
	v_and_b32_e32 v243, 0xffff0000, v243
	s_nop 1
	s_waitcnt lgkmcnt(8)
	v_mfma_f32_16x16x32_bf16 v[240:243], v[176:179], v[224:227], v[240:243]
	s_waitcnt lgkmcnt(6)
	v_mfma_f32_16x16x32_bf16 v[244:247], v[184:187], v[232:235], 0
	s_waitcnt lgkmcnt(5)
	v_mfma_f32_16x16x32_bf16 v[248:251], v[192:195], v[232:235], 0
	s_waitcnt lgkmcnt(3)
	v_mfma_f32_16x16x32_bf16 v[240:243], v[180:183], v[228:231], v[240:243]
	s_waitcnt lgkmcnt(1)
	v_mfma_f32_16x16x32_bf16 v[244:247], v[188:191], v[236:239], v[244:247]
	s_waitcnt lgkmcnt(0)
	v_mfma_f32_16x16x32_bf16 v[248:251], v[196:199], v[236:239], v[248:251]
	s_nop 7
	v_cvt_pk_bf16_f32 v176, v240, v241
	v_cvt_pk_bf16_f32 v177, v242, v243
	v_cvt_pk_bf16_f32 v184, v244, v245
	v_cvt_pk_bf16_f32 v185, v246, v247
	v_cvt_pk_bf16_f32 v192, v248, v249
	v_cvt_pk_bf16_f32 v193, v250, v251
	ds_write_b64 v127, v[176:177] offset:18432
	ds_write_b64 v127, v[184:185] offset:0
	ds_write_b16 v151, v184 offset:9216
	ds_write_b16_d16_hi v151, v184 offset:9360
	ds_write_b16 v151, v185 offset:9504
	ds_write_b16_d16_hi v151, v185 offset:9648
	ds_write_b64 v129, v[102:103] offset:18432
	ds_write_b64 v129, v[192:193] offset:0
	ds_write_b16 v152, v192 offset:9216
	ds_write_b16_d16_hi v152, v192 offset:9360
	ds_write_b16 v152, v193 offset:9504
	ds_write_b16_d16_hi v152, v193 offset:9648
	s_waitcnt lgkmcnt(0)
	s_barrier
	ds_read_b64 v[242:243], v127 offset:18432
	ds_read_b128 v[176:179], v173 offset:0
	ds_read_b128 v[224:227], v107 offset:18432
	ds_read_b128 v[180:183], v173 offset:64
	ds_read_b128 v[228:231], v107 offset:18496
	s_waitcnt lgkmcnt(4)
	v_lshlrev_b32_e32 v240, 16, v242
	v_and_b32_e32 v241, 0xffff0000, v242
	v_lshlrev_b32_e32 v242, 16, v243
	v_and_b32_e32 v243, 0xffff0000, v243
	s_nop 1
	s_waitcnt lgkmcnt(2)
	v_mfma_f32_16x16x32_bf16 v[240:243], v[176:179], v[224:227], v[240:243]
	s_waitcnt lgkmcnt(0)
	v_mfma_f32_16x16x32_bf16 v[240:243], v[180:183], v[228:231], v[240:243]
	s_nop 7
	v_cvt_pk_bf16_f32 v176, v240, v241
	v_cvt_pk_bf16_f32 v177, v242, v243
	ds_write_b64 v97, v[176:177] offset:18432
	ds_write_b64 v98, v[102:103] offset:18432
	s_waitcnt lgkmcnt(0)
	s_barrier
	s_branch .La2_done
